# hot loop heads (10 GEMM k-loops + attention main loop) aligned to 64 B with .p2align 6, on top of carry-loop batching
# speedup vs baseline: 1.0014x; 1.0014x over previous
;     ...
;     f32x4 acc[2][2][4][2];
; #pragma unroll
;     for (int a = 0; a < 2; ++a)
; #pragma unroll
;         for (int b = 0; b < 2; ++b)
; #pragma unroll
;             for (int m = 0; m < 4; ++m)
; #pragma unroll
;                 for (int n = 0; n < 2; ++n) acc[a][b][m][n] = (f32x4){0.f, 0.f, 0.f, 0.f};
;     ...
;     for (;;) {
;         const bool has_next = S.next(ui + 1, nxt);
;         const char* nA = has_next ? PG8_ABASE(nxt) : cA; const char* nB = has_next ? (const char*)g.Bt + (size_t)nxt.pn * tstepB : cB;
; #pragma unroll 1
;         for (int t = 0; t < nt; t += 2) {
;             const bool last = (t == nt - 2);
;             const char* a1 = cA + (size_t)(t + 1) * kstep;
;             const char* a2 = last ? nA : cA + (size_t)(t + 2) * kstep; const char* b2 = last ? nB : cB + (size_t)(t + 2) * kstep;
;             const char* a3 = a2 + kstep; const char* b3 = b2 + kstep;
.LBB0_164:
	v_lshl_add_u64 v[6:7], v[148:149], 0, s[52:53]
	v_lshl_add_u64 v[154:155], v[4:5], 0, s[4:5]
	v_mov_b32_e32 v4, 0
	v_lshl_add_u64 v[150:151], v[6:7], 0, v[140:141]
	v_lshl_add_u64 v[152:153], v[6:7], 0, v[142:143]
	s_mov_b32 s60, -2
	s_mov_b64 s[38:39], 0
	v_mov_b32_e32 v5, v4
	v_mov_b32_e32 v6, v4
	v_mov_b32_e32 v7, v4
	v_mov_b32_e32 v8, v4
	v_mov_b32_e32 v9, v4
	v_mov_b32_e32 v10, v4
	v_mov_b32_e32 v11, v4
	v_mov_b32_e32 v20, v4
	v_mov_b32_e32 v21, v4
	v_mov_b32_e32 v22, v4
	v_mov_b32_e32 v23, v4
	v_mov_b32_e32 v24, v4
	v_mov_b32_e32 v25, v4
	v_mov_b32_e32 v26, v4
	v_mov_b32_e32 v27, v4
	v_mov_b32_e32 v36, v4
	v_mov_b32_e32 v37, v4
	v_mov_b32_e32 v38, v4
	v_mov_b32_e32 v39, v4
	v_mov_b32_e32 v40, v4
	v_mov_b32_e32 v41, v4
	v_mov_b32_e32 v42, v4
	v_mov_b32_e32 v43, v4
	v_mov_b32_e32 v52, v4
	v_mov_b32_e32 v53, v4
	v_mov_b32_e32 v54, v4
	v_mov_b32_e32 v55, v4
	v_mov_b32_e32 v56, v4
	v_mov_b32_e32 v57, v4
	v_mov_b32_e32 v58, v4
	v_mov_b32_e32 v59, v4
	v_mov_b32_e32 v12, v4
	v_mov_b32_e32 v13, v4
	v_mov_b32_e32 v14, v4
	v_mov_b32_e32 v15, v4
	v_mov_b32_e32 v16, v4
	v_mov_b32_e32 v17, v4
	v_mov_b32_e32 v18, v4
	v_mov_b32_e32 v19, v4
	v_mov_b32_e32 v28, v4
	v_mov_b32_e32 v29, v4
	v_mov_b32_e32 v30, v4
	v_mov_b32_e32 v31, v4
	v_mov_b32_e32 v32, v4
	v_mov_b32_e32 v33, v4
	v_mov_b32_e32 v34, v4
	v_mov_b32_e32 v35, v4
	v_mov_b32_e32 v44, v4
	v_mov_b32_e32 v45, v4
	v_mov_b32_e32 v46, v4
	v_mov_b32_e32 v47, v4
	v_mov_b32_e32 v48, v4
	v_mov_b32_e32 v49, v4
	v_mov_b32_e32 v50, v4
	v_mov_b32_e32 v51, v4
	v_mov_b32_e32 v60, v4
	v_mov_b32_e32 v61, v4
	v_mov_b32_e32 v62, v4
	v_mov_b32_e32 v63, v4
	v_mov_b32_e32 v64, v4
	v_mov_b32_e32 v65, v4
	v_mov_b32_e32 v66, v4
	v_mov_b32_e32 v67, v4
	v_mov_b32_e32 v68, v4
	v_mov_b32_e32 v69, v4
	v_mov_b32_e32 v70, v4
	v_mov_b32_e32 v71, v4
	v_mov_b32_e32 v72, v4
	v_mov_b32_e32 v73, v4
	v_mov_b32_e32 v74, v4
	v_mov_b32_e32 v75, v4
	v_mov_b32_e32 v84, v4
	v_mov_b32_e32 v85, v4
	v_mov_b32_e32 v86, v4
	v_mov_b32_e32 v87, v4
	v_mov_b32_e32 v88, v4
	v_mov_b32_e32 v89, v4
	v_mov_b32_e32 v90, v4
	v_mov_b32_e32 v91, v4
	v_mov_b32_e32 v100, v4
	v_mov_b32_e32 v101, v4
	v_mov_b32_e32 v102, v4
	v_mov_b32_e32 v103, v4
	v_mov_b32_e32 v104, v4
	v_mov_b32_e32 v105, v4
	v_mov_b32_e32 v106, v4
	v_mov_b32_e32 v107, v4
	v_mov_b32_e32 v116, v4
	v_mov_b32_e32 v117, v4
	v_mov_b32_e32 v118, v4
	v_mov_b32_e32 v119, v4
	v_mov_b32_e32 v120, v4
	v_mov_b32_e32 v121, v4
	v_mov_b32_e32 v122, v4
	v_mov_b32_e32 v123, v4
	v_mov_b32_e32 v76, v4
	v_mov_b32_e32 v77, v4
	v_mov_b32_e32 v78, v4
	v_mov_b32_e32 v79, v4
	v_mov_b32_e32 v80, v4
	v_mov_b32_e32 v81, v4
	v_mov_b32_e32 v82, v4
	v_mov_b32_e32 v83, v4
	v_mov_b32_e32 v92, v4
	v_mov_b32_e32 v93, v4
	v_mov_b32_e32 v94, v4
	v_mov_b32_e32 v95, v4
	v_mov_b32_e32 v96, v4
	v_mov_b32_e32 v97, v4
	v_mov_b32_e32 v98, v4
	v_mov_b32_e32 v99, v4
	v_mov_b32_e32 v108, v4
	v_mov_b32_e32 v109, v4
	v_mov_b32_e32 v110, v4
	v_mov_b32_e32 v111, v4
	v_mov_b32_e32 v112, v4
	v_mov_b32_e32 v113, v4
	v_mov_b32_e32 v114, v4
	v_mov_b32_e32 v115, v4
	v_mov_b32_e32 v124, v4
	v_mov_b32_e32 v125, v4
	v_mov_b32_e32 v126, v4
	v_mov_b32_e32 v127, v4
	v_mov_b32_e32 v128, v4
	v_mov_b32_e32 v129, v4
	v_mov_b32_e32 v130, v4
	v_mov_b32_e32 v131, v4
	v_add_u32_e32 v246, 0x10000, v158
	v_add_u32_e32 v247, 0x14000, v158
	v_add_u32_e32 v248, 0x18000, v158
	v_add_u32_e32 v249, 0x1c000, v158
	.p2align 6

;     ...
; #pragma unroll
;         for (int a = 0; a < 2; ++a)
; #pragma unroll
;             for (int b = 0; b < 2; ++b)
; #pragma unroll
;                 for (int m = 0; m < 4; ++m)
; #pragma unroll
;                     for (int n = 0; n < 2; ++n) acc[a][b][m][n] = (f32x4){0.f, 0.f, 0.f, 0.f};
;         cur = nxt; cA = nA; cB = nB; ++ui;
.LBB0_415:
	v_mov_b32_e32 v4, 0
	s_mov_b64 s[44:45], 0
	s_mov_b64 s[28:29], -1
	s_mov_b64 s[34:35], 0
	v_mov_b32_e32 v5, v4
	v_mov_b32_e32 v6, v4
	v_mov_b32_e32 v7, v4
	v_mov_b32_e32 v12, v4
	v_mov_b32_e32 v13, v4
	v_mov_b32_e32 v14, v4
	v_mov_b32_e32 v15, v4
	v_mov_b32_e32 v44, v4
	v_mov_b32_e32 v45, v4
	v_mov_b32_e32 v46, v4
	v_mov_b32_e32 v47, v4
	v_mov_b32_e32 v52, v4
	v_mov_b32_e32 v53, v4
	v_mov_b32_e32 v54, v4
	v_mov_b32_e32 v55, v4
	v_mov_b32_e32 v60, v4
	v_mov_b32_e32 v61, v4
	v_mov_b32_e32 v62, v4
	v_mov_b32_e32 v63, v4
	v_mov_b32_e32 v68, v4
	v_mov_b32_e32 v69, v4
	v_mov_b32_e32 v70, v4
	v_mov_b32_e32 v71, v4
	v_mov_b32_e32 v76, v4
	v_mov_b32_e32 v77, v4
	v_mov_b32_e32 v78, v4
	v_mov_b32_e32 v79, v4
	v_mov_b32_e32 v84, v4
	v_mov_b32_e32 v85, v4
	v_mov_b32_e32 v86, v4
	v_mov_b32_e32 v87, v4
	v_mov_b32_e32 v8, v4
	v_mov_b32_e32 v9, v4
	v_mov_b32_e32 v10, v4
	v_mov_b32_e32 v11, v4
	v_mov_b32_e32 v16, v4
	v_mov_b32_e32 v17, v4
	v_mov_b32_e32 v18, v4
	v_mov_b32_e32 v19, v4
	v_mov_b32_e32 v48, v4
	v_mov_b32_e32 v49, v4
	v_mov_b32_e32 v50, v4
	v_mov_b32_e32 v51, v4
	v_mov_b32_e32 v56, v4
	v_mov_b32_e32 v57, v4
	v_mov_b32_e32 v58, v4
	v_mov_b32_e32 v59, v4
	v_mov_b32_e32 v64, v4
	v_mov_b32_e32 v65, v4
	v_mov_b32_e32 v66, v4
	v_mov_b32_e32 v67, v4
	v_mov_b32_e32 v72, v4
	v_mov_b32_e32 v73, v4
	v_mov_b32_e32 v74, v4
	v_mov_b32_e32 v75, v4
	v_mov_b32_e32 v80, v4
	v_mov_b32_e32 v81, v4
	v_mov_b32_e32 v82, v4
	v_mov_b32_e32 v83, v4
	v_mov_b32_e32 v88, v4
	v_mov_b32_e32 v89, v4
	v_mov_b32_e32 v90, v4
	v_mov_b32_e32 v91, v4
	v_mov_b32_e32 v92, v4
	v_mov_b32_e32 v93, v4
	v_mov_b32_e32 v94, v4
	v_mov_b32_e32 v95, v4
	v_mov_b32_e32 v100, v4
	v_mov_b32_e32 v101, v4
	v_mov_b32_e32 v102, v4
	v_mov_b32_e32 v103, v4
	v_mov_b32_e32 v108, v4
	v_mov_b32_e32 v109, v4
	v_mov_b32_e32 v110, v4
	v_mov_b32_e32 v111, v4
	v_mov_b32_e32 v116, v4
	v_mov_b32_e32 v117, v4
	v_mov_b32_e32 v118, v4
	v_mov_b32_e32 v119, v4
	v_mov_b32_e32 v124, v4
	v_mov_b32_e32 v125, v4
	v_mov_b32_e32 v126, v4
	v_mov_b32_e32 v127, v4
	v_mov_b32_e32 v132, v4
	v_mov_b32_e32 v133, v4
	v_mov_b32_e32 v134, v4
	v_mov_b32_e32 v135, v4
	v_mov_b32_e32 v140, v4
	v_mov_b32_e32 v141, v4
	v_mov_b32_e32 v142, v4
	v_mov_b32_e32 v143, v4
	v_mov_b32_e32 v148, v4
	v_mov_b32_e32 v149, v4
	v_mov_b32_e32 v150, v4
	v_mov_b32_e32 v151, v4
	v_mov_b32_e32 v96, v4
	v_mov_b32_e32 v97, v4
	v_mov_b32_e32 v98, v4
	v_mov_b32_e32 v99, v4
	v_mov_b32_e32 v104, v4
	v_mov_b32_e32 v105, v4
	v_mov_b32_e32 v106, v4
	v_mov_b32_e32 v107, v4
	v_mov_b32_e32 v112, v4
	v_mov_b32_e32 v113, v4
	v_mov_b32_e32 v114, v4
	v_mov_b32_e32 v115, v4
	v_mov_b32_e32 v120, v4
	v_mov_b32_e32 v121, v4
	v_mov_b32_e32 v122, v4
	v_mov_b32_e32 v123, v4
	v_mov_b32_e32 v128, v4
	v_mov_b32_e32 v129, v4
	v_mov_b32_e32 v130, v4
	v_mov_b32_e32 v131, v4
	v_mov_b32_e32 v136, v4
	v_mov_b32_e32 v137, v4
	v_mov_b32_e32 v138, v4
	v_mov_b32_e32 v139, v4
	v_mov_b32_e32 v144, v4
	v_mov_b32_e32 v145, v4
	v_mov_b32_e32 v146, v4
	v_mov_b32_e32 v147, v4
	v_mov_b32_e32 v152, v4
	v_mov_b32_e32 v153, v4
	v_mov_b32_e32 v154, v4
	v_mov_b32_e32 v155, v4
	.p2align 6

;     ...
;     for (;;) {
;         const bool has_next = S.next(ui + 1, nxt);
;         const char* nA = has_next ? PG8_ABASE(nxt) : cA; const char* nB = has_next ? (const char*)g.Bt + (size_t)nxt.pn * tstepB : cB;
; #pragma unroll 1
;         for (int t = 0; t < nt; t += 2) {
;             const bool last = (t == nt - 2);
;             const char* a1 = cA + (size_t)(t + 1) * kstep;
;             const char* a2 = last ? nA : cA + (size_t)(t + 2) * kstep; const char* b2 = last ? nB : cB + (size_t)(t + 2) * kstep;
;             const char* a3 = a2 + kstep; const char* b3 = b2 + kstep;
;     ...
; #pragma unroll
;         for (int a = 0; a < 2; ++a)
; #pragma unroll
;             for (int b = 0; b < 2; ++b)
; #pragma unroll
;                 for (int m = 0; m < 4; ++m)
; #pragma unroll
;                     for (int n = 0; n < 2; ++n) acc[a][b][m][n] = (f32x4){0.f, 0.f, 0.f, 0.f};
.LBB0_439:
	v_lshl_add_u64 v[6:7], v[180:181], 0, s[52:53]
	v_mov_b32_e32 v36, 0
	v_lshl_add_u64 v[182:183], v[6:7], 0, v[172:173]
	v_lshl_add_u64 v[184:185], v[6:7], 0, v[174:175]
	v_lshl_add_u64 v[186:187], v[4:5], 0, s[4:5]
	s_mov_b32 s62, -2
	s_mov_b64 s[38:39], 0
	v_mov_b32_e32 v37, v36
	v_mov_b32_e32 v38, v36
	v_mov_b32_e32 v39, v36
	v_mov_b32_e32 v40, v36
	v_mov_b32_e32 v41, v36
	v_mov_b32_e32 v42, v36
	v_mov_b32_e32 v43, v36
	v_mov_b32_e32 v48, v36
	v_mov_b32_e32 v49, v36
	v_mov_b32_e32 v50, v36
	v_mov_b32_e32 v51, v36
	v_mov_b32_e32 v56, v36
	v_mov_b32_e32 v57, v36
	v_mov_b32_e32 v58, v36
	v_mov_b32_e32 v59, v36
	v_mov_b32_e32 v64, v36
	v_mov_b32_e32 v65, v36
	v_mov_b32_e32 v66, v36
	v_mov_b32_e32 v67, v36
	v_mov_b32_e32 v72, v36
	v_mov_b32_e32 v73, v36
	v_mov_b32_e32 v74, v36
	v_mov_b32_e32 v75, v36
	v_mov_b32_e32 v80, v36
	v_mov_b32_e32 v81, v36
	v_mov_b32_e32 v82, v36
	v_mov_b32_e32 v83, v36
	v_mov_b32_e32 v88, v36
	v_mov_b32_e32 v89, v36
	v_mov_b32_e32 v90, v36
	v_mov_b32_e32 v91, v36
	v_mov_b32_e32 v44, v36
	v_mov_b32_e32 v45, v36
	v_mov_b32_e32 v46, v36
	v_mov_b32_e32 v47, v36
	v_mov_b32_e32 v52, v36
	v_mov_b32_e32 v53, v36
	v_mov_b32_e32 v54, v36
	v_mov_b32_e32 v55, v36
	v_mov_b32_e32 v60, v36
	v_mov_b32_e32 v61, v36
	v_mov_b32_e32 v62, v36
	v_mov_b32_e32 v63, v36
	v_mov_b32_e32 v68, v36
	v_mov_b32_e32 v69, v36
	v_mov_b32_e32 v70, v36
	v_mov_b32_e32 v71, v36
	v_mov_b32_e32 v76, v36
	v_mov_b32_e32 v77, v36
	v_mov_b32_e32 v78, v36
	v_mov_b32_e32 v79, v36
	v_mov_b32_e32 v84, v36
	v_mov_b32_e32 v85, v36
	v_mov_b32_e32 v86, v36
	v_mov_b32_e32 v87, v36
	v_mov_b32_e32 v92, v36
	v_mov_b32_e32 v93, v36
	v_mov_b32_e32 v94, v36
	v_mov_b32_e32 v95, v36
	v_mov_b32_e32 v96, v36
	v_mov_b32_e32 v97, v36
	v_mov_b32_e32 v98, v36
	v_mov_b32_e32 v99, v36
	v_mov_b32_e32 v100, v36
	v_mov_b32_e32 v101, v36
	v_mov_b32_e32 v102, v36
	v_mov_b32_e32 v103, v36
	v_mov_b32_e32 v104, v36
	v_mov_b32_e32 v105, v36
	v_mov_b32_e32 v106, v36
	v_mov_b32_e32 v107, v36
	v_mov_b32_e32 v112, v36
	v_mov_b32_e32 v113, v36
	v_mov_b32_e32 v114, v36
	v_mov_b32_e32 v115, v36
	v_mov_b32_e32 v120, v36
	v_mov_b32_e32 v121, v36
	v_mov_b32_e32 v122, v36
	v_mov_b32_e32 v123, v36
	v_mov_b32_e32 v128, v36
	v_mov_b32_e32 v129, v36
	v_mov_b32_e32 v130, v36
	v_mov_b32_e32 v131, v36
	v_mov_b32_e32 v136, v36
	v_mov_b32_e32 v137, v36
	v_mov_b32_e32 v138, v36
	v_mov_b32_e32 v139, v36
	v_mov_b32_e32 v144, v36
	v_mov_b32_e32 v145, v36
	v_mov_b32_e32 v146, v36
	v_mov_b32_e32 v147, v36
	v_mov_b32_e32 v152, v36
	v_mov_b32_e32 v153, v36
	v_mov_b32_e32 v154, v36
	v_mov_b32_e32 v155, v36
	v_mov_b32_e32 v108, v36
	v_mov_b32_e32 v109, v36
	v_mov_b32_e32 v110, v36
	v_mov_b32_e32 v111, v36
	v_mov_b32_e32 v116, v36
	v_mov_b32_e32 v117, v36
	v_mov_b32_e32 v118, v36
	v_mov_b32_e32 v119, v36
	v_mov_b32_e32 v124, v36
	v_mov_b32_e32 v125, v36
	v_mov_b32_e32 v126, v36
	v_mov_b32_e32 v127, v36
	v_mov_b32_e32 v132, v36
	v_mov_b32_e32 v133, v36
	v_mov_b32_e32 v134, v36
	v_mov_b32_e32 v135, v36
	v_mov_b32_e32 v140, v36
	v_mov_b32_e32 v141, v36
	v_mov_b32_e32 v142, v36
	v_mov_b32_e32 v143, v36
	v_mov_b32_e32 v148, v36
	v_mov_b32_e32 v149, v36
	v_mov_b32_e32 v150, v36
	v_mov_b32_e32 v151, v36
	v_mov_b32_e32 v156, v36
	v_mov_b32_e32 v157, v36
	v_mov_b32_e32 v158, v36
	v_mov_b32_e32 v159, v36
	v_mov_b32_e32 v160, v36
	v_mov_b32_e32 v161, v36
	v_mov_b32_e32 v162, v36
	v_mov_b32_e32 v163, v36
	v_add_u32_e32 v204, 0x10000, v210
	v_add_u32_e32 v205, 0x14000, v210
	v_add_u32_e32 v206, 0x18000, v210
	v_add_u32_e32 v207, 0x1c000, v210
	.p2align 6

;     ...
; #pragma unroll
;         for (int a = 0; a < 2; ++a)
; #pragma unroll
;             for (int b = 0; b < 2; ++b)
; #pragma unroll
;                 for (int m = 0; m < 4; ++m)
; #pragma unroll
;                     for (int n = 0; n < 2; ++n) acc[a][b][m][n] = (f32x4){0.f, 0.f, 0.f, 0.f};
;         cur = nxt; cA = nA; cB = nB; ++ui;
.LBB0_467:
	v_mov_b32_e32 v20, 0
	s_mov_b64 s[48:49], 0
	s_mov_b64 s[38:39], -1
	s_mov_b64 s[46:47], 0
	v_mov_b32_e32 v21, v20
	v_mov_b32_e32 v22, v20
	v_mov_b32_e32 v23, v20
	v_mov_b32_e32 v24, v20
	v_mov_b32_e32 v25, v20
	v_mov_b32_e32 v26, v20
	v_mov_b32_e32 v27, v20
	v_mov_b32_e32 v32, v20
	v_mov_b32_e32 v33, v20
	v_mov_b32_e32 v34, v20
	v_mov_b32_e32 v35, v20
	v_mov_b32_e32 v40, v20
	v_mov_b32_e32 v41, v20
	v_mov_b32_e32 v42, v20
	v_mov_b32_e32 v43, v20
	v_mov_b32_e32 v48, v20
	v_mov_b32_e32 v49, v20
	v_mov_b32_e32 v50, v20
	v_mov_b32_e32 v51, v20
	v_mov_b32_e32 v56, v20
	v_mov_b32_e32 v57, v20
	v_mov_b32_e32 v58, v20
	v_mov_b32_e32 v59, v20
	v_mov_b32_e32 v64, v20
	v_mov_b32_e32 v65, v20
	v_mov_b32_e32 v66, v20
	v_mov_b32_e32 v67, v20
	v_mov_b32_e32 v72, v20
	v_mov_b32_e32 v73, v20
	v_mov_b32_e32 v74, v20
	v_mov_b32_e32 v75, v20
	v_mov_b32_e32 v28, v20
	v_mov_b32_e32 v29, v20
	v_mov_b32_e32 v30, v20
	v_mov_b32_e32 v31, v20
	v_mov_b32_e32 v36, v20
	v_mov_b32_e32 v37, v20
	v_mov_b32_e32 v38, v20
	v_mov_b32_e32 v39, v20
	v_mov_b32_e32 v44, v20
	v_mov_b32_e32 v45, v20
	v_mov_b32_e32 v46, v20
	v_mov_b32_e32 v47, v20
	v_mov_b32_e32 v52, v20
	v_mov_b32_e32 v53, v20
	v_mov_b32_e32 v54, v20
	v_mov_b32_e32 v55, v20
	v_mov_b32_e32 v60, v20
	v_mov_b32_e32 v61, v20
	v_mov_b32_e32 v62, v20
	v_mov_b32_e32 v63, v20
	v_mov_b32_e32 v68, v20
	v_mov_b32_e32 v69, v20
	v_mov_b32_e32 v70, v20
	v_mov_b32_e32 v71, v20
	v_mov_b32_e32 v76, v20
	v_mov_b32_e32 v77, v20
	v_mov_b32_e32 v78, v20
	v_mov_b32_e32 v79, v20
	v_mov_b32_e32 v80, v20
	v_mov_b32_e32 v81, v20
	v_mov_b32_e32 v82, v20
	v_mov_b32_e32 v83, v20
	v_mov_b32_e32 v84, v20
	v_mov_b32_e32 v85, v20
	v_mov_b32_e32 v86, v20
	v_mov_b32_e32 v87, v20
	v_mov_b32_e32 v88, v20
	v_mov_b32_e32 v89, v20
	v_mov_b32_e32 v90, v20
	v_mov_b32_e32 v91, v20
	v_mov_b32_e32 v96, v20
	v_mov_b32_e32 v97, v20
	v_mov_b32_e32 v98, v20
	v_mov_b32_e32 v99, v20
	v_mov_b32_e32 v104, v20
	v_mov_b32_e32 v105, v20
	v_mov_b32_e32 v106, v20
	v_mov_b32_e32 v107, v20
	v_mov_b32_e32 v112, v20
	v_mov_b32_e32 v113, v20
	v_mov_b32_e32 v114, v20
	v_mov_b32_e32 v115, v20
	v_mov_b32_e32 v120, v20
	v_mov_b32_e32 v121, v20
	v_mov_b32_e32 v122, v20
	v_mov_b32_e32 v123, v20
	v_mov_b32_e32 v128, v20
	v_mov_b32_e32 v129, v20
	v_mov_b32_e32 v130, v20
	v_mov_b32_e32 v131, v20
	v_mov_b32_e32 v136, v20
	v_mov_b32_e32 v137, v20
	v_mov_b32_e32 v138, v20
	v_mov_b32_e32 v139, v20
	v_mov_b32_e32 v92, v20
	v_mov_b32_e32 v93, v20
	v_mov_b32_e32 v94, v20
	v_mov_b32_e32 v95, v20
	v_mov_b32_e32 v100, v20
	v_mov_b32_e32 v101, v20
	v_mov_b32_e32 v102, v20
	v_mov_b32_e32 v103, v20
	v_mov_b32_e32 v108, v20
	v_mov_b32_e32 v109, v20
	v_mov_b32_e32 v110, v20
	v_mov_b32_e32 v111, v20
	v_mov_b32_e32 v116, v20
	v_mov_b32_e32 v117, v20
	v_mov_b32_e32 v118, v20
	v_mov_b32_e32 v119, v20
	v_mov_b32_e32 v124, v20
	v_mov_b32_e32 v125, v20
	v_mov_b32_e32 v126, v20
	v_mov_b32_e32 v127, v20
	v_mov_b32_e32 v132, v20
	v_mov_b32_e32 v133, v20
	v_mov_b32_e32 v134, v20
	v_mov_b32_e32 v135, v20
	v_mov_b32_e32 v140, v20
	v_mov_b32_e32 v141, v20
	v_mov_b32_e32 v142, v20
	v_mov_b32_e32 v143, v20
	v_mov_b32_e32 v144, v20
	v_mov_b32_e32 v145, v20
	v_mov_b32_e32 v146, v20
	v_mov_b32_e32 v147, v20
	.p2align 6

; #define SBAR() __builtin_amdgcn_sched_barrier(0)
; #define ATT_MFMA_SETTLE() asm volatile("s_nop 15\n\ts_nop 15" ::: "memory")
; #define ATT_BAR() asm volatile("s_waitcnt lgkmcnt(0)\n\ts_barrier" ::: "memory")
; __device__ __forceinline__ void sm_raise(f32x16& p0, f32x16& p1, f32x16& nm, float delta) {
;   const f32x2 d2 = {delta, delta};
; #pragma unroll
;   for (int r = 0; r < 16; r += 2) { const f32x2 t = (f32x2){p0[r], p0[r + 1]} - d2; p0[r] = t.x; p0[r + 1] = t.y; const f32x2 w = (f32x2){p1[r], p1[r + 1]} - d2; p1[r] = w.x; p1[r + 1] = w.y;
;     const f32x2 n_ = (f32x2){nm[r], nm[r + 1]} - d2; nm[r] = n_.x; nm[r + 1] = n_.y; }
; }
; __device__ __forceinline__ void partialSM(f32x16& p0, f32x16& p1, f32x16& nm, float& alpha, bool first) {
;   float pmax, pmb;
;   asm("v_max3_f32 %0, %1, %2, %3" : "=v"(pmax) : "v"(p0[0]), "v"(p0[1]), "v"(p1[0]));
;   asm("v_max3_f32 %0, %1, %2, %3" : "=v"(pmb) : "v"(p0[2]), "v"(p0[3]), "v"(p1[1]));
;   asm("v_max3_f32 %0, %1, %2, %3" : "=v"(pmax) : "v"(pmax), "v"(p1[2]), "v"(p1[3]));
; #pragma unroll
;   for (int r = 4; r < 16; r += 4) {
;     asm("v_max3_f32 %0, %1, %2, %3" : "=v"(pmax) : "v"(pmax), "v"(p0[r]), "v"(p0[r + 1]));
;     asm("v_max3_f32 %0, %1, %2, %3" : "=v"(pmb) : "v"(pmb), "v"(p0[r + 2]), "v"(p0[r + 3]));
;     asm("v_max3_f32 %0, %1, %2, %3" : "=v"(pmax) : "v"(pmax), "v"(p1[r]), "v"(p1[r + 1]));
;     asm("v_max3_f32 %0, %1, %2, %3" : "=v"(pmb) : "v"(pmb), "v"(p1[r + 2]), "v"(p1[r + 3])); }
;   pmax = fmaxf(pmax, pmb);
;   { auto rr = __builtin_amdgcn_permlane32_swap(__float_as_uint(pmax), __float_as_uint(pmax), false, false);
;     pmax = fmaxf(__uint_as_float(rr[0]), __uint_as_float(rr[1])); }
;   if (first) { alpha = 1.f; sm_raise(p0, p1, nm, pmax - SEED6); }
;   else if (__builtin_expect(__all(pmax <= THRP), 1)) alpha = 1.f;
;   else { const float delta = fmaxf(pmax - SEED6, 0.f); alpha = __builtin_amdgcn_exp2f(-delta); sm_raise(p0, p1, nm, delta); }
; }
; __device__ __forceinline__ void attn_unit(const bf16_t* __restrict__ Qb, const unsigned char* __restrict__ Kn, const unsigned char* __restrict__ Vp, const unsigned char* __restrict__ Kp, ...
;     ...
;   KLOAD(0); qk_mma(pA0, pA1, k0, k1, KR_lds, qf, nm, r32, hi, sc); ATT_MFMA_SETTLE(); SBAR(); KLOAD(1); partialSM(pA0, pA1, nm, alA, true);
;   WAIT_TILES2(); ATT_BAR();
;   ISSUE(5, 5 * KVBLK);
;   int s0 = 1;
.LBB0_649:
	s_and_b32 s7, s7, 0x3fffffc0
	s_lshl_b32 s7, s7, 2
	s_add_i32 s7, s7, 0
	v_max_f32_e32 v0, v36, v36
	v_max_f32_e32 v1, v37, v37
	s_add_i32 s7, s7, 0x1e000
	s_add_i32 s57, s8, 0x18000
	v_max_f32_e32 v0, v0, v1
	s_add_u32 s58, s3, s82
	v_add_f32_e32 v0, 0xbfe75768, v0
	s_addc_u32 s59, s72, s83
	v_sub_f32_e32 v115, v35, v0
	v_sub_f32_e32 v114, v34, v0
	v_sub_f32_e32 v113, v33, v0
	v_sub_f32_e32 v112, v32, v0
	v_sub_f32_e32 v111, v31, v0
	v_sub_f32_e32 v110, v30, v0
	v_sub_f32_e32 v109, v29, v0
	v_sub_f32_e32 v108, v28, v0
	v_sub_f32_e32 v107, v27, v0
	v_sub_f32_e32 v106, v26, v0
	v_sub_f32_e32 v105, v25, v0
	v_sub_f32_e32 v104, v24, v0
	v_sub_f32_e32 v103, v23, v0
	v_sub_f32_e32 v102, v22, v0
	v_sub_f32_e32 v101, v21, v0
	v_sub_f32_e32 v100, v20, v0
	v_sub_f32_e32 v99, v19, v0
	v_sub_f32_e32 v98, v18, v0
	v_sub_f32_e32 v97, v17, v0
	v_sub_f32_e32 v96, v16, v0
	v_sub_f32_e32 v95, v15, v0
	v_sub_f32_e32 v94, v14, v0
	v_sub_f32_e32 v93, v13, v0
	v_sub_f32_e32 v92, v12, v0
	v_sub_f32_e32 v91, v11, v0
	v_sub_f32_e32 v90, v10, v0
	v_sub_f32_e32 v89, v9, v0
	v_sub_f32_e32 v88, v8, v0
	v_sub_f32_e32 v87, v7, v0
	v_sub_f32_e32 v86, v6, v0
	v_sub_f32_e32 v85, v5, v0
	v_sub_f32_e32 v84, v4, v0
	v_sub_f32_e32 v68, 0x3fe75768, v0
	v_add_u32_e32 v0, 0, v230
	v_lshl_add_u64 v[210:211], s[58:59], 0, v[2:3]
	s_add_u32 s58, s76, s49
	v_add_u32_e32 v239, v0, v231
	v_add_u32_e32 v240, v0, v232
	s_addc_u32 s59, s77, 0
	s_lshl_b32 s2, s2, 15
	v_lshlrev_b32_e32 v0, 12, v55
	v_or3_b32 v2, s2, v0, v56
	v_lshl_add_u64 v[0:1], s[58:59], 0, v[2:3]
	s_lshl_b32 s58, s74, 20
	s_lshl_b64 s[38:39], s[38:39], 7
	s_add_u32 s38, s58, s38
	s_addc_u32 s39, 0, s39
	v_add_u32_e32 v2, s9, v54
	v_lshl_add_u64 v[4:5], s[38:39], 0, v[2:3]
	v_mov_b32_e32 v14, v3
	v_mov_b32_e32 v15, v3
	v_lshl_add_u64 v[212:213], s[34:35], 0, v[0:1]
	v_lshl_add_u64 v[214:215], s[44:45], 0, v[4:5]
	v_lshl_add_u64 v[216:217], s[46:47], 0, v[0:1]
	v_lshl_add_u64 v[218:219], s[40:41], 0, v[4:5]
	v_mov_b32_e32 v0, v3
	v_mov_b32_e32 v1, v3
	v_mov_b32_e32 v2, v3
	v_mov_b32_e32 v4, v3
	v_mov_b32_e32 v5, v3
	v_mov_b32_e32 v6, v3
	v_mov_b32_e32 v7, v3
	v_mov_b32_e32 v8, v3
	v_mov_b32_e32 v9, v3
	v_mov_b32_e32 v10, v3
	v_mov_b32_e32 v11, v3
	v_mov_b32_e32 v12, v3
	v_mov_b32_e32 v13, v3
	v_mov_b64_e32 v[66:67], v[14:15]
	v_mov_b64_e32 v[50:51], v[14:15]
	v_mov_b64_e32 v[34:35], v[14:15]
	v_mov_b64_e32 v[64:65], v[12:13]
	v_mov_b64_e32 v[62:63], v[10:11]
	v_mov_b64_e32 v[60:61], v[8:9]
	v_mov_b64_e32 v[58:59], v[6:7]
	v_mov_b64_e32 v[56:57], v[4:5]
	v_mov_b64_e32 v[54:55], v[2:3]
	v_mov_b64_e32 v[52:53], v[0:1]
	v_mov_b64_e32 v[48:49], v[12:13]
	v_mov_b64_e32 v[46:47], v[10:11]
	v_mov_b64_e32 v[44:45], v[8:9]
	v_mov_b64_e32 v[42:43], v[6:7]
	v_mov_b64_e32 v[40:41], v[4:5]
	v_mov_b64_e32 v[38:39], v[2:3]
	v_mov_b64_e32 v[36:37], v[0:1]
	v_mov_b64_e32 v[32:33], v[12:13]
	v_mov_b64_e32 v[30:31], v[10:11]
	v_mov_b64_e32 v[28:29], v[8:9]
	v_mov_b64_e32 v[26:27], v[6:7]
	v_mov_b64_e32 v[24:25], v[4:5]
	v_mov_b64_e32 v[22:23], v[2:3]
	v_mov_b64_e32 v[20:21], v[0:1]
	v_mov_b64_e32 v[18:19], v[14:15]
	v_mov_b32_e32 v69, v68
	v_mov_b32_e32 v70, v68
	v_mov_b32_e32 v71, v68
	v_mov_b32_e32 v72, v68
	v_mov_b32_e32 v73, v68
	v_mov_b32_e32 v74, v68
	v_mov_b32_e32 v75, v68
	v_mov_b32_e32 v76, v68
	v_mov_b32_e32 v77, v68
	v_mov_b32_e32 v78, v68
	v_mov_b32_e32 v79, v68
	v_mov_b32_e32 v80, v68
	v_mov_b32_e32 v81, v68
	v_mov_b32_e32 v82, v68
	v_mov_b32_e32 v83, v68
	v_lshl_add_u32 v228, v220, 2, s7
	v_lshlrev_b32_e32 v227, 4, v221
	s_mov_b32 s2, 7
	v_mov_b32_e32 v241, 1.0
	v_mov_b32_e32 v229, 0
	s_mov_b32 s62, 1
	v_mov_b64_e32 v[16:17], v[12:13]
	v_mov_b64_e32 v[14:15], v[10:11]
	v_mov_b64_e32 v[12:13], v[8:9]
	v_mov_b64_e32 v[10:11], v[6:7]
	v_mov_b64_e32 v[8:9], v[4:5]
	v_mov_b64_e32 v[6:7], v[2:3]
	v_mov_b64_e32 v[4:5], v[0:1]
	s_movk_i32 s74, 0x3000
	.p2align 6

;     ...
;     for (;;) {
;         const bool has_next = S.next(ui + 1, nxt);
;         const char* nA = has_next ? PG8_ABASE(nxt) : cA; const char* nB = has_next ? (const char*)g.Bt + (size_t)nxt.pn * tstepB : cB;
; #pragma unroll 1
;         for (int t = 0; t < nt; t += 2) {
;             const bool last = (t == nt - 2);
;             const char* a1 = cA + (size_t)(t + 1) * kstep;
;             const char* a2 = last ? nA : cA + (size_t)(t + 2) * kstep; const char* b2 = last ? nB : cB + (size_t)(t + 2) * kstep;
;             const char* a3 = a2 + kstep; const char* b3 = b2 + kstep;
;     ...
; #pragma unroll
;         for (int a = 0; a < 2; ++a)
; #pragma unroll
;             for (int b = 0; b < 2; ++b)
; #pragma unroll
;                 for (int m = 0; m < 4; ++m)
; #pragma unroll
;                     for (int n = 0; n < 2; ++n) acc[a][b][m][n] = (f32x4){0.f, 0.f, 0.f, 0.f};
.LBB0_782:
	v_lshl_add_u64 v[6:7], v[148:149], 0, s[52:53]
	v_lshl_add_u64 v[154:155], v[4:5], 0, s[4:5]
	v_mov_b32_e32 v4, 0
	v_lshl_add_u64 v[150:151], v[6:7], 0, v[140:141]
	v_lshl_add_u64 v[152:153], v[6:7], 0, v[142:143]
	s_mov_b32 s38, -2
	s_mov_b64 s[28:29], 0
	v_mov_b32_e32 v5, v4
	v_mov_b32_e32 v6, v4
	v_mov_b32_e32 v7, v4
	v_mov_b32_e32 v8, v4
	v_mov_b32_e32 v9, v4
	v_mov_b32_e32 v10, v4
	v_mov_b32_e32 v11, v4
	v_mov_b32_e32 v20, v4
	v_mov_b32_e32 v21, v4
	v_mov_b32_e32 v22, v4
	v_mov_b32_e32 v23, v4
	v_mov_b32_e32 v24, v4
	v_mov_b32_e32 v25, v4
	v_mov_b32_e32 v26, v4
	v_mov_b32_e32 v27, v4
	v_mov_b32_e32 v36, v4
	v_mov_b32_e32 v37, v4
	v_mov_b32_e32 v38, v4
	v_mov_b32_e32 v39, v4
	v_mov_b32_e32 v40, v4
	v_mov_b32_e32 v41, v4
	v_mov_b32_e32 v42, v4
	v_mov_b32_e32 v43, v4
	v_mov_b32_e32 v52, v4
	v_mov_b32_e32 v53, v4
	v_mov_b32_e32 v54, v4
	v_mov_b32_e32 v55, v4
	v_mov_b32_e32 v56, v4
	v_mov_b32_e32 v57, v4
	v_mov_b32_e32 v58, v4
	v_mov_b32_e32 v59, v4
	v_mov_b32_e32 v12, v4
	v_mov_b32_e32 v13, v4
	v_mov_b32_e32 v14, v4
	v_mov_b32_e32 v15, v4
	v_mov_b32_e32 v16, v4
	v_mov_b32_e32 v17, v4
	v_mov_b32_e32 v18, v4
	v_mov_b32_e32 v19, v4
	v_mov_b32_e32 v28, v4
	v_mov_b32_e32 v29, v4
	v_mov_b32_e32 v30, v4
	v_mov_b32_e32 v31, v4
	v_mov_b32_e32 v32, v4
	v_mov_b32_e32 v33, v4
	v_mov_b32_e32 v34, v4
	v_mov_b32_e32 v35, v4
	v_mov_b32_e32 v44, v4
	v_mov_b32_e32 v45, v4
	v_mov_b32_e32 v46, v4
	v_mov_b32_e32 v47, v4
	v_mov_b32_e32 v48, v4
	v_mov_b32_e32 v49, v4
	v_mov_b32_e32 v50, v4
	v_mov_b32_e32 v51, v4
	v_mov_b32_e32 v60, v4
	v_mov_b32_e32 v61, v4
	v_mov_b32_e32 v62, v4
	v_mov_b32_e32 v63, v4
	v_mov_b32_e32 v64, v4
	v_mov_b32_e32 v65, v4
	v_mov_b32_e32 v66, v4
	v_mov_b32_e32 v67, v4
	v_mov_b32_e32 v68, v4
	v_mov_b32_e32 v69, v4
	v_mov_b32_e32 v70, v4
	v_mov_b32_e32 v71, v4
	v_mov_b32_e32 v72, v4
	v_mov_b32_e32 v73, v4
	v_mov_b32_e32 v74, v4
	v_mov_b32_e32 v75, v4
	v_mov_b32_e32 v84, v4
	v_mov_b32_e32 v85, v4
	v_mov_b32_e32 v86, v4
	v_mov_b32_e32 v87, v4
	v_mov_b32_e32 v88, v4
	v_mov_b32_e32 v89, v4
	v_mov_b32_e32 v90, v4
	v_mov_b32_e32 v91, v4
	v_mov_b32_e32 v100, v4
	v_mov_b32_e32 v101, v4
	v_mov_b32_e32 v102, v4
	v_mov_b32_e32 v103, v4
	v_mov_b32_e32 v104, v4
	v_mov_b32_e32 v105, v4
	v_mov_b32_e32 v106, v4
	v_mov_b32_e32 v107, v4
	v_mov_b32_e32 v116, v4
	v_mov_b32_e32 v117, v4
	v_mov_b32_e32 v118, v4
	v_mov_b32_e32 v119, v4
	v_mov_b32_e32 v120, v4
	v_mov_b32_e32 v121, v4
	v_mov_b32_e32 v122, v4
	v_mov_b32_e32 v123, v4
	v_mov_b32_e32 v76, v4
	v_mov_b32_e32 v77, v4
	v_mov_b32_e32 v78, v4
	v_mov_b32_e32 v79, v4
	v_mov_b32_e32 v80, v4
	v_mov_b32_e32 v81, v4
	v_mov_b32_e32 v82, v4
	v_mov_b32_e32 v83, v4
	v_mov_b32_e32 v92, v4
	v_mov_b32_e32 v93, v4
	v_mov_b32_e32 v94, v4
	v_mov_b32_e32 v95, v4
	v_mov_b32_e32 v96, v4
	v_mov_b32_e32 v97, v4
	v_mov_b32_e32 v98, v4
	v_mov_b32_e32 v99, v4
	v_mov_b32_e32 v108, v4
	v_mov_b32_e32 v109, v4
	v_mov_b32_e32 v110, v4
	v_mov_b32_e32 v111, v4
	v_mov_b32_e32 v112, v4
	v_mov_b32_e32 v113, v4
	v_mov_b32_e32 v114, v4
	v_mov_b32_e32 v115, v4
	v_mov_b32_e32 v124, v4
	v_mov_b32_e32 v125, v4
	v_mov_b32_e32 v126, v4
	v_mov_b32_e32 v127, v4
	v_mov_b32_e32 v128, v4
	v_mov_b32_e32 v129, v4
	v_mov_b32_e32 v130, v4
	v_mov_b32_e32 v131, v4
	v_add_u32_e32 v246, 0x10000, v157
	v_add_u32_e32 v247, 0x14000, v157
	v_add_u32_e32 v248, 0x18000, v157
	v_add_u32_e32 v249, 0x1c000, v157
	.p2align 6

;     ...
;     for (;;) {
;         const bool has_next = S.next(ui + 1, nxt);
;         const char* nA = has_next ? PG8_ABASE(nxt) : cA; const char* nB = has_next ? (const char*)g.Bt + (size_t)nxt.pn * tstepB : cB;
; #pragma unroll 1
;         for (int t = 0; t < nt; t += 2) {
;             const bool last = (t == nt - 2);
;             const char* a1 = cA + (size_t)(t + 1) * kstep;
;             const char* a2 = last ? nA : cA + (size_t)(t + 2) * kstep; const char* b2 = last ? nB : cB + (size_t)(t + 2) * kstep;
;             const char* a3 = a2 + kstep; const char* b3 = b2 + kstep;
;     ...
; #pragma unroll
;         for (int a = 0; a < 2; ++a)
; #pragma unroll
;             for (int b = 0; b < 2; ++b)
; #pragma unroll
;                 for (int m = 0; m < 4; ++m)
; #pragma unroll
;                     for (int n = 0; n < 2; ++n) acc[a][b][m][n] = (f32x4){0.f, 0.f, 0.f, 0.f};
.LBB0_817:
	v_lshl_add_u64 v[6:7], v[180:181], 0, s[52:53]
	v_mov_b32_e32 v36, 0
	v_lshl_add_u64 v[182:183], v[6:7], 0, v[172:173]
	v_lshl_add_u64 v[184:185], v[6:7], 0, v[174:175]
	v_lshl_add_u64 v[186:187], v[4:5], 0, s[4:5]
	s_mov_b32 s42, -2
	s_mov_b64 s[28:29], 0
	v_mov_b32_e32 v37, v36
	v_mov_b32_e32 v38, v36
	v_mov_b32_e32 v39, v36
	v_mov_b32_e32 v40, v36
	v_mov_b32_e32 v41, v36
	v_mov_b32_e32 v42, v36
	v_mov_b32_e32 v43, v36
	v_mov_b32_e32 v52, v36
	v_mov_b32_e32 v53, v36
	v_mov_b32_e32 v54, v36
	v_mov_b32_e32 v55, v36
	v_mov_b32_e32 v56, v36
	v_mov_b32_e32 v57, v36
	v_mov_b32_e32 v58, v36
	v_mov_b32_e32 v59, v36
	v_mov_b32_e32 v68, v36
	v_mov_b32_e32 v69, v36
	v_mov_b32_e32 v70, v36
	v_mov_b32_e32 v71, v36
	v_mov_b32_e32 v72, v36
	v_mov_b32_e32 v73, v36
	v_mov_b32_e32 v74, v36
	v_mov_b32_e32 v75, v36
	v_mov_b32_e32 v84, v36
	v_mov_b32_e32 v85, v36
	v_mov_b32_e32 v86, v36
	v_mov_b32_e32 v87, v36
	v_mov_b32_e32 v88, v36
	v_mov_b32_e32 v89, v36
	v_mov_b32_e32 v90, v36
	v_mov_b32_e32 v91, v36
	v_mov_b32_e32 v44, v36
	v_mov_b32_e32 v45, v36
	v_mov_b32_e32 v46, v36
	v_mov_b32_e32 v47, v36
	v_mov_b32_e32 v48, v36
	v_mov_b32_e32 v49, v36
	v_mov_b32_e32 v50, v36
	v_mov_b32_e32 v51, v36
	v_mov_b32_e32 v60, v36
	v_mov_b32_e32 v61, v36
	v_mov_b32_e32 v62, v36
	v_mov_b32_e32 v63, v36
	v_mov_b32_e32 v64, v36
	v_mov_b32_e32 v65, v36
	v_mov_b32_e32 v66, v36
	v_mov_b32_e32 v67, v36
	v_mov_b32_e32 v76, v36
	v_mov_b32_e32 v77, v36
	v_mov_b32_e32 v78, v36
	v_mov_b32_e32 v79, v36
	v_mov_b32_e32 v80, v36
	v_mov_b32_e32 v81, v36
	v_mov_b32_e32 v82, v36
	v_mov_b32_e32 v83, v36
	v_mov_b32_e32 v92, v36
	v_mov_b32_e32 v93, v36
	v_mov_b32_e32 v94, v36
	v_mov_b32_e32 v95, v36
	v_mov_b32_e32 v96, v36
	v_mov_b32_e32 v97, v36
	v_mov_b32_e32 v98, v36
	v_mov_b32_e32 v99, v36
	v_mov_b32_e32 v100, v36
	v_mov_b32_e32 v101, v36
	v_mov_b32_e32 v102, v36
	v_mov_b32_e32 v103, v36
	v_mov_b32_e32 v104, v36
	v_mov_b32_e32 v105, v36
	v_mov_b32_e32 v106, v36
	v_mov_b32_e32 v107, v36
	v_mov_b32_e32 v116, v36
	v_mov_b32_e32 v117, v36
	v_mov_b32_e32 v118, v36
	v_mov_b32_e32 v119, v36
	v_mov_b32_e32 v120, v36
	v_mov_b32_e32 v121, v36
	v_mov_b32_e32 v122, v36
	v_mov_b32_e32 v123, v36
	v_mov_b32_e32 v132, v36
	v_mov_b32_e32 v133, v36
	v_mov_b32_e32 v134, v36
	v_mov_b32_e32 v135, v36
	v_mov_b32_e32 v136, v36
	v_mov_b32_e32 v137, v36
	v_mov_b32_e32 v138, v36
	v_mov_b32_e32 v139, v36
	v_mov_b32_e32 v148, v36
	v_mov_b32_e32 v149, v36
	v_mov_b32_e32 v150, v36
	v_mov_b32_e32 v151, v36
	v_mov_b32_e32 v152, v36
	v_mov_b32_e32 v153, v36
	v_mov_b32_e32 v154, v36
	v_mov_b32_e32 v155, v36
	v_mov_b32_e32 v108, v36
	v_mov_b32_e32 v109, v36
	v_mov_b32_e32 v110, v36
	v_mov_b32_e32 v111, v36
	v_mov_b32_e32 v112, v36
	v_mov_b32_e32 v113, v36
	v_mov_b32_e32 v114, v36
	v_mov_b32_e32 v115, v36
	v_mov_b32_e32 v124, v36
	v_mov_b32_e32 v125, v36
	v_mov_b32_e32 v126, v36
	v_mov_b32_e32 v127, v36
	v_mov_b32_e32 v128, v36
	v_mov_b32_e32 v129, v36
	v_mov_b32_e32 v130, v36
	v_mov_b32_e32 v131, v36
	v_mov_b32_e32 v140, v36
	v_mov_b32_e32 v141, v36
	v_mov_b32_e32 v142, v36
	v_mov_b32_e32 v143, v36
	v_mov_b32_e32 v144, v36
	v_mov_b32_e32 v145, v36
	v_mov_b32_e32 v146, v36
	v_mov_b32_e32 v147, v36
	v_mov_b32_e32 v156, v36
	v_mov_b32_e32 v157, v36
	v_mov_b32_e32 v158, v36
	v_mov_b32_e32 v159, v36
	v_mov_b32_e32 v160, v36
	v_mov_b32_e32 v161, v36
	v_mov_b32_e32 v162, v36
	v_mov_b32_e32 v163, v36
	v_add_u32_e32 v213, 0x10000, v210
	v_add_u32_e32 v250, 0x14000, v210
	v_add_u32_e32 v251, 0x18000, v210
	.p2align 6

;     ...
;     for (;;) {
;         const bool has_next = S.next(ui + 1, nxt);
;         const char* nA = has_next ? PG8_ABASE(nxt) : cA; const char* nB = has_next ? (const char*)g.Bt + (size_t)nxt.pn * tstepB : cB;
; #pragma unroll 1
;         for (int t = 0; t < nt; t += 2) {
;             const bool last = (t == nt - 2);
;             const char* a1 = cA + (size_t)(t + 1) * kstep;
;             const char* a2 = last ? nA : cA + (size_t)(t + 2) * kstep; const char* b2 = last ? nB : cB + (size_t)(t + 2) * kstep;
;             const char* a3 = a2 + kstep; const char* b3 = b2 + kstep;
;     ...
; #pragma unroll
;         for (int a = 0; a < 2; ++a)
; #pragma unroll
;             for (int b = 0; b < 2; ++b)
; #pragma unroll
;                 for (int m = 0; m < 4; ++m)
; #pragma unroll
;                     for (int n = 0; n < 2; ++n) acc[a][b][m][n] = (f32x4){0.f, 0.f, 0.f, 0.f};
.LBB0_911:
	v_lshl_add_u64 v[6:7], v[148:149], 0, s[52:53]
	v_lshl_add_u64 v[154:155], v[4:5], 0, s[4:5]
	v_mov_b32_e32 v4, 0
	v_lshl_add_u64 v[150:151], v[6:7], 0, v[140:141]
	v_lshl_add_u64 v[152:153], v[6:7], 0, v[142:143]
	s_mov_b32 s58, -2
	s_mov_b64 s[38:39], 0
	v_mov_b32_e32 v5, v4
	v_mov_b32_e32 v6, v4
	v_mov_b32_e32 v7, v4
	v_mov_b32_e32 v8, v4
	v_mov_b32_e32 v9, v4
	v_mov_b32_e32 v10, v4
	v_mov_b32_e32 v11, v4
	v_mov_b32_e32 v12, v4
	v_mov_b32_e32 v13, v4
	v_mov_b32_e32 v14, v4
	v_mov_b32_e32 v15, v4
	v_mov_b32_e32 v16, v4
	v_mov_b32_e32 v17, v4
	v_mov_b32_e32 v18, v4
	v_mov_b32_e32 v19, v4
	v_mov_b32_e32 v20, v4
	v_mov_b32_e32 v21, v4
	v_mov_b32_e32 v22, v4
	v_mov_b32_e32 v23, v4
	v_mov_b32_e32 v24, v4
	v_mov_b32_e32 v25, v4
	v_mov_b32_e32 v26, v4
	v_mov_b32_e32 v27, v4
	v_mov_b32_e32 v28, v4
	v_mov_b32_e32 v29, v4
	v_mov_b32_e32 v30, v4
	v_mov_b32_e32 v31, v4
	v_mov_b32_e32 v32, v4
	v_mov_b32_e32 v33, v4
	v_mov_b32_e32 v34, v4
	v_mov_b32_e32 v35, v4
	v_mov_b32_e32 v36, v4
	v_mov_b32_e32 v37, v4
	v_mov_b32_e32 v38, v4
	v_mov_b32_e32 v39, v4
	v_mov_b32_e32 v40, v4
	v_mov_b32_e32 v41, v4
	v_mov_b32_e32 v42, v4
	v_mov_b32_e32 v43, v4
	v_mov_b32_e32 v44, v4
	v_mov_b32_e32 v45, v4
	v_mov_b32_e32 v46, v4
	v_mov_b32_e32 v47, v4
	v_mov_b32_e32 v48, v4
	v_mov_b32_e32 v49, v4
	v_mov_b32_e32 v50, v4
	v_mov_b32_e32 v51, v4
	v_mov_b32_e32 v52, v4
	v_mov_b32_e32 v53, v4
	v_mov_b32_e32 v54, v4
	v_mov_b32_e32 v55, v4
	v_mov_b32_e32 v56, v4
	v_mov_b32_e32 v57, v4
	v_mov_b32_e32 v58, v4
	v_mov_b32_e32 v59, v4
	v_mov_b32_e32 v60, v4
	v_mov_b32_e32 v61, v4
	v_mov_b32_e32 v62, v4
	v_mov_b32_e32 v63, v4
	v_mov_b32_e32 v64, v4
	v_mov_b32_e32 v65, v4
	v_mov_b32_e32 v66, v4
	v_mov_b32_e32 v67, v4
	v_mov_b32_e32 v68, v4
	v_mov_b32_e32 v69, v4
	v_mov_b32_e32 v70, v4
	v_mov_b32_e32 v71, v4
	v_mov_b32_e32 v72, v4
	v_mov_b32_e32 v73, v4
	v_mov_b32_e32 v74, v4
	v_mov_b32_e32 v75, v4
	v_mov_b32_e32 v76, v4
	v_mov_b32_e32 v77, v4
	v_mov_b32_e32 v78, v4
	v_mov_b32_e32 v79, v4
	v_mov_b32_e32 v80, v4
	v_mov_b32_e32 v81, v4
	v_mov_b32_e32 v82, v4
	v_mov_b32_e32 v83, v4
	v_mov_b32_e32 v84, v4
	v_mov_b32_e32 v85, v4
	v_mov_b32_e32 v86, v4
	v_mov_b32_e32 v87, v4
	v_mov_b32_e32 v88, v4
	v_mov_b32_e32 v89, v4
	v_mov_b32_e32 v90, v4
	v_mov_b32_e32 v91, v4
	v_mov_b32_e32 v92, v4
	v_mov_b32_e32 v93, v4
	v_mov_b32_e32 v94, v4
	v_mov_b32_e32 v95, v4
	v_mov_b32_e32 v96, v4
	v_mov_b32_e32 v97, v4
	v_mov_b32_e32 v98, v4
	v_mov_b32_e32 v99, v4
	v_mov_b32_e32 v100, v4
	v_mov_b32_e32 v101, v4
	v_mov_b32_e32 v102, v4
	v_mov_b32_e32 v103, v4
	v_mov_b32_e32 v104, v4
	v_mov_b32_e32 v105, v4
	v_mov_b32_e32 v106, v4
	v_mov_b32_e32 v107, v4
	v_mov_b32_e32 v108, v4
	v_mov_b32_e32 v109, v4
	v_mov_b32_e32 v110, v4
	v_mov_b32_e32 v111, v4
	v_mov_b32_e32 v112, v4
	v_mov_b32_e32 v113, v4
	v_mov_b32_e32 v114, v4
	v_mov_b32_e32 v115, v4
	v_mov_b32_e32 v116, v4
	v_mov_b32_e32 v117, v4
	v_mov_b32_e32 v118, v4
	v_mov_b32_e32 v119, v4
	v_mov_b32_e32 v120, v4
	v_mov_b32_e32 v121, v4
	v_mov_b32_e32 v122, v4
	v_mov_b32_e32 v123, v4
	v_mov_b32_e32 v124, v4
	v_mov_b32_e32 v125, v4
	v_mov_b32_e32 v126, v4
	v_mov_b32_e32 v127, v4
	v_mov_b32_e32 v128, v4
	v_mov_b32_e32 v129, v4
	v_mov_b32_e32 v130, v4
	v_mov_b32_e32 v131, v4
	v_add_u32_e32 v246, 0x10000, v158
	v_add_u32_e32 v247, 0x14000, v158
	v_add_u32_e32 v248, 0x18000, v158
	v_add_u32_e32 v249, 0x1c000, v158
	.p2align 6

;     ...
;     for (;;) {
;         const bool has_next = S.next(ui + 1, nxt);
;         const char* nA = has_next ? PG8_ABASE(nxt) : cA; const char* nB = has_next ? (const char*)g.Bt + (size_t)nxt.pn * tstepB : cB;
; #pragma unroll 1
;         for (int t = 0; t < nt; t += 2) {
;             const bool last = (t == nt - 2);
;             const char* a1 = cA + (size_t)(t + 1) * kstep;
;             const char* a2 = last ? nA : cA + (size_t)(t + 2) * kstep; const char* b2 = last ? nB : cB + (size_t)(t + 2) * kstep;
;             const char* a3 = a2 + kstep; const char* b3 = b2 + kstep;
;     ...
; #pragma unroll
;         for (int a = 0; a < 2; ++a)
; #pragma unroll
;             for (int b = 0; b < 2; ++b)
; #pragma unroll
;                 for (int m = 0; m < 4; ++m)
; #pragma unroll
;                     for (int n = 0; n < 2; ++n) acc[a][b][m][n] = (f32x4){0.f, 0.f, 0.f, 0.f};
.LBB0_1045:
	v_lshl_add_u64 v[158:159], v[0:1], 0, s[20:21]
	v_mov_b32_e32 v0, 0
	v_lshl_add_u64 v[154:155], v[152:153], 0, v[140:141]
	v_lshl_add_u64 v[156:157], v[152:153], 0, v[142:143]
	s_mov_b32 s38, -2
	s_mov_b64 s[24:25], 0
	v_mov_b32_e32 v1, v0
	v_mov_b32_e32 v2, v0
	v_mov_b32_e32 v3, v0
	v_mov_b32_e32 v4, v0
	v_mov_b32_e32 v5, v0
	v_mov_b32_e32 v6, v0
	v_mov_b32_e32 v7, v0
	v_mov_b32_e32 v8, v0
	v_mov_b32_e32 v9, v0
	v_mov_b32_e32 v10, v0
	v_mov_b32_e32 v11, v0
	v_mov_b32_e32 v12, v0
	v_mov_b32_e32 v13, v0
	v_mov_b32_e32 v14, v0
	v_mov_b32_e32 v15, v0
	v_mov_b32_e32 v16, v0
	v_mov_b32_e32 v17, v0
	v_mov_b32_e32 v18, v0
	v_mov_b32_e32 v19, v0
	v_mov_b32_e32 v20, v0
	v_mov_b32_e32 v21, v0
	v_mov_b32_e32 v22, v0
	v_mov_b32_e32 v23, v0
	v_mov_b32_e32 v24, v0
	v_mov_b32_e32 v25, v0
	v_mov_b32_e32 v26, v0
	v_mov_b32_e32 v27, v0
	v_mov_b32_e32 v28, v0
	v_mov_b32_e32 v29, v0
	v_mov_b32_e32 v30, v0
	v_mov_b32_e32 v31, v0
	v_mov_b32_e32 v32, v0
	v_mov_b32_e32 v33, v0
	v_mov_b32_e32 v34, v0
	v_mov_b32_e32 v35, v0
	v_mov_b32_e32 v36, v0
	v_mov_b32_e32 v37, v0
	v_mov_b32_e32 v38, v0
	v_mov_b32_e32 v39, v0
	v_mov_b32_e32 v40, v0
	v_mov_b32_e32 v41, v0
	v_mov_b32_e32 v42, v0
	v_mov_b32_e32 v43, v0
	v_mov_b32_e32 v44, v0
	v_mov_b32_e32 v45, v0
	v_mov_b32_e32 v46, v0
	v_mov_b32_e32 v47, v0
	v_mov_b32_e32 v48, v0
	v_mov_b32_e32 v49, v0
	v_mov_b32_e32 v50, v0
	v_mov_b32_e32 v51, v0
	v_mov_b32_e32 v52, v0
	v_mov_b32_e32 v53, v0
	v_mov_b32_e32 v54, v0
	v_mov_b32_e32 v55, v0
	v_mov_b32_e32 v56, v0
	v_mov_b32_e32 v57, v0
	v_mov_b32_e32 v58, v0
	v_mov_b32_e32 v59, v0
	v_mov_b32_e32 v60, v0
	v_mov_b32_e32 v61, v0
	v_mov_b32_e32 v62, v0
	v_mov_b32_e32 v63, v0
	v_mov_b32_e32 v64, v0
	v_mov_b32_e32 v65, v0
	v_mov_b32_e32 v66, v0
	v_mov_b32_e32 v67, v0
	v_mov_b32_e32 v68, v0
	v_mov_b32_e32 v69, v0
	v_mov_b32_e32 v70, v0
	v_mov_b32_e32 v71, v0
	v_mov_b32_e32 v72, v0
	v_mov_b32_e32 v73, v0
	v_mov_b32_e32 v74, v0
	v_mov_b32_e32 v75, v0
	v_mov_b32_e32 v76, v0
	v_mov_b32_e32 v77, v0
	v_mov_b32_e32 v78, v0
	v_mov_b32_e32 v79, v0
	v_mov_b32_e32 v80, v0
	v_mov_b32_e32 v81, v0
	v_mov_b32_e32 v82, v0
	v_mov_b32_e32 v83, v0
	v_mov_b32_e32 v84, v0
	v_mov_b32_e32 v85, v0
	v_mov_b32_e32 v86, v0
	v_mov_b32_e32 v87, v0
	v_mov_b32_e32 v88, v0
	v_mov_b32_e32 v89, v0
	v_mov_b32_e32 v90, v0
	v_mov_b32_e32 v91, v0
	v_mov_b32_e32 v92, v0
	v_mov_b32_e32 v93, v0
	v_mov_b32_e32 v94, v0
	v_mov_b32_e32 v95, v0
	v_mov_b32_e32 v96, v0
	v_mov_b32_e32 v97, v0
	v_mov_b32_e32 v98, v0
	v_mov_b32_e32 v99, v0
	v_mov_b32_e32 v100, v0
	v_mov_b32_e32 v101, v0
	v_mov_b32_e32 v102, v0
	v_mov_b32_e32 v103, v0
	v_mov_b32_e32 v104, v0
	v_mov_b32_e32 v105, v0
	v_mov_b32_e32 v106, v0
	v_mov_b32_e32 v107, v0
	v_mov_b32_e32 v108, v0
	v_mov_b32_e32 v109, v0
	v_mov_b32_e32 v110, v0
	v_mov_b32_e32 v111, v0
	v_mov_b32_e32 v112, v0
	v_mov_b32_e32 v113, v0
	v_mov_b32_e32 v114, v0
	v_mov_b32_e32 v115, v0
	v_mov_b32_e32 v116, v0
	v_mov_b32_e32 v117, v0
	v_mov_b32_e32 v118, v0
	v_mov_b32_e32 v119, v0
	v_mov_b32_e32 v120, v0
	v_mov_b32_e32 v121, v0
	v_mov_b32_e32 v122, v0
	v_mov_b32_e32 v123, v0
	v_mov_b32_e32 v124, v0
	v_mov_b32_e32 v125, v0
	v_mov_b32_e32 v126, v0
	v_mov_b32_e32 v127, v0
	v_add_u32_e32 v248, 0x18000, v162
	v_add_u32_e32 v249, 0x1c000, v162
	.p2align 6

;     ...
;     for (;;) {
;         const bool has_next = S.next(ui + 1, nxt);
;         const char* nA = has_next ? PG8_ABASE(nxt) : cA; const char* nB = has_next ? (const char*)g.Bt + (size_t)nxt.pn * tstepB : cB;
; #pragma unroll 1
;         for (int t = 0; t < nt; t += 2) {
;             const bool last = (t == nt - 2);
;             const char* a1 = cA + (size_t)(t + 1) * kstep;
;             const char* a2 = last ? nA : cA + (size_t)(t + 2) * kstep; const char* b2 = last ? nB : cB + (size_t)(t + 2) * kstep;
;             const char* a3 = a2 + kstep; const char* b3 = b2 + kstep;
;     ...
; #pragma unroll
;         for (int a = 0; a < 2; ++a)
; #pragma unroll
;             for (int b = 0; b < 2; ++b)
; #pragma unroll
;                 for (int m = 0; m < 4; ++m)
; #pragma unroll
;                     for (int n = 0; n < 2; ++n) acc[a][b][m][n] = (f32x4){0.f, 0.f, 0.f, 0.f};
.LBB0_1065:
	v_lshl_add_u64 v[158:159], v[0:1], 0, s[16:17]
	v_mov_b32_e32 v0, 0
	v_lshl_add_u64 v[154:155], v[152:153], 0, v[140:141]
	v_lshl_add_u64 v[156:157], v[152:153], 0, v[142:143]
	s_mov_b32 s38, -2
	s_mov_b64 s[18:19], 0
	v_mov_b32_e32 v1, v0
	v_mov_b32_e32 v2, v0
	v_mov_b32_e32 v3, v0
	v_mov_b32_e32 v4, v0
	v_mov_b32_e32 v5, v0
	v_mov_b32_e32 v6, v0
	v_mov_b32_e32 v7, v0
	v_mov_b32_e32 v16, v0
	v_mov_b32_e32 v17, v0
	v_mov_b32_e32 v18, v0
	v_mov_b32_e32 v19, v0
	v_mov_b32_e32 v20, v0
	v_mov_b32_e32 v21, v0
	v_mov_b32_e32 v22, v0
	v_mov_b32_e32 v23, v0
	v_mov_b32_e32 v32, v0
	v_mov_b32_e32 v33, v0
	v_mov_b32_e32 v34, v0
	v_mov_b32_e32 v35, v0
	v_mov_b32_e32 v36, v0
	v_mov_b32_e32 v37, v0
	v_mov_b32_e32 v38, v0
	v_mov_b32_e32 v39, v0
	v_mov_b32_e32 v48, v0
	v_mov_b32_e32 v49, v0
	v_mov_b32_e32 v50, v0
	v_mov_b32_e32 v51, v0
	v_mov_b32_e32 v52, v0
	v_mov_b32_e32 v53, v0
	v_mov_b32_e32 v54, v0
	v_mov_b32_e32 v55, v0
	v_mov_b32_e32 v8, v0
	v_mov_b32_e32 v9, v0
	v_mov_b32_e32 v10, v0
	v_mov_b32_e32 v11, v0
	v_mov_b32_e32 v12, v0
	v_mov_b32_e32 v13, v0
	v_mov_b32_e32 v14, v0
	v_mov_b32_e32 v15, v0
	v_mov_b32_e32 v24, v0
	v_mov_b32_e32 v25, v0
	v_mov_b32_e32 v26, v0
	v_mov_b32_e32 v27, v0
	v_mov_b32_e32 v28, v0
	v_mov_b32_e32 v29, v0
	v_mov_b32_e32 v30, v0
	v_mov_b32_e32 v31, v0
	v_mov_b32_e32 v40, v0
	v_mov_b32_e32 v41, v0
	v_mov_b32_e32 v42, v0
	v_mov_b32_e32 v43, v0
	v_mov_b32_e32 v44, v0
	v_mov_b32_e32 v45, v0
	v_mov_b32_e32 v46, v0
	v_mov_b32_e32 v47, v0
	v_mov_b32_e32 v56, v0
	v_mov_b32_e32 v57, v0
	v_mov_b32_e32 v58, v0
	v_mov_b32_e32 v59, v0
	v_mov_b32_e32 v60, v0
	v_mov_b32_e32 v61, v0
	v_mov_b32_e32 v62, v0
	v_mov_b32_e32 v63, v0
	v_mov_b32_e32 v64, v0
	v_mov_b32_e32 v65, v0
	v_mov_b32_e32 v66, v0
	v_mov_b32_e32 v67, v0
	v_mov_b32_e32 v68, v0
	v_mov_b32_e32 v69, v0
	v_mov_b32_e32 v70, v0
	v_mov_b32_e32 v71, v0
	v_mov_b32_e32 v80, v0
	v_mov_b32_e32 v81, v0
	v_mov_b32_e32 v82, v0
	v_mov_b32_e32 v83, v0
	v_mov_b32_e32 v84, v0
	v_mov_b32_e32 v85, v0
	v_mov_b32_e32 v86, v0
	v_mov_b32_e32 v87, v0
	v_mov_b32_e32 v96, v0
	v_mov_b32_e32 v97, v0
	v_mov_b32_e32 v98, v0
	v_mov_b32_e32 v99, v0
	v_mov_b32_e32 v100, v0
	v_mov_b32_e32 v101, v0
	v_mov_b32_e32 v102, v0
	v_mov_b32_e32 v103, v0
	v_mov_b32_e32 v112, v0
	v_mov_b32_e32 v113, v0
	v_mov_b32_e32 v114, v0
	v_mov_b32_e32 v115, v0
	v_mov_b32_e32 v116, v0
	v_mov_b32_e32 v117, v0
	v_mov_b32_e32 v118, v0
	v_mov_b32_e32 v119, v0
	v_mov_b32_e32 v72, v0
	v_mov_b32_e32 v73, v0
	v_mov_b32_e32 v74, v0
	v_mov_b32_e32 v75, v0
	v_mov_b32_e32 v76, v0
	v_mov_b32_e32 v77, v0
	v_mov_b32_e32 v78, v0
	v_mov_b32_e32 v79, v0
	v_mov_b32_e32 v88, v0
	v_mov_b32_e32 v89, v0
	v_mov_b32_e32 v90, v0
	v_mov_b32_e32 v91, v0
	v_mov_b32_e32 v92, v0
	v_mov_b32_e32 v93, v0
	v_mov_b32_e32 v94, v0
	v_mov_b32_e32 v95, v0
	v_mov_b32_e32 v104, v0
	v_mov_b32_e32 v105, v0
	v_mov_b32_e32 v106, v0
	v_mov_b32_e32 v107, v0
	v_mov_b32_e32 v108, v0
	v_mov_b32_e32 v109, v0
	v_mov_b32_e32 v110, v0
	v_mov_b32_e32 v111, v0
	v_mov_b32_e32 v120, v0
	v_mov_b32_e32 v121, v0
	v_mov_b32_e32 v122, v0
	v_mov_b32_e32 v123, v0
	v_mov_b32_e32 v124, v0
	v_mov_b32_e32 v125, v0
	v_mov_b32_e32 v126, v0
	v_mov_b32_e32 v127, v0
	v_add_u32_e32 v248, 0x18000, v162
	v_add_u32_e32 v249, 0x1c000, v162
	.p2align 6

;     ...
;     for (;;) {
;         const bool has_next = S.next(ui + 1, nxt);
;         const char* nA = has_next ? PG8_ABASE(nxt) : cA; const char* nB = has_next ? (const char*)g.Bt + (size_t)nxt.pn * tstepB : cB;
; #pragma unroll 1
;         for (int t = 0; t < nt; t += 2) {
;             const bool last = (t == nt - 2);
;             const char* a1 = cA + (size_t)(t + 1) * kstep;
;             const char* a2 = last ? nA : cA + (size_t)(t + 2) * kstep; const char* b2 = last ? nB : cB + (size_t)(t + 2) * kstep;
;             const char* a3 = a2 + kstep; const char* b3 = b2 + kstep;
;     ...
; #pragma unroll
;         for (int a = 0; a < 2; ++a)
; #pragma unroll
;             for (int b = 0; b < 2; ++b)
; #pragma unroll
;                 for (int m = 0; m < 4; ++m)
; #pragma unroll
;                     for (int n = 0; n < 2; ++n) acc[a][b][m][n] = (f32x4){0.f, 0.f, 0.f, 0.f};
.LBB0_1147:
	v_lshl_add_u64 v[158:159], v[0:1], 0, s[16:17]
	v_mov_b32_e32 v0, 0
	v_lshl_add_u64 v[154:155], v[152:153], 0, v[140:141]
	v_lshl_add_u64 v[156:157], v[152:153], 0, v[142:143]
	s_mov_b32 s20, -2
	s_mov_b64 s[18:19], 0
	v_mov_b32_e32 v1, v0
	v_mov_b32_e32 v2, v0
	v_mov_b32_e32 v3, v0
	v_mov_b32_e32 v4, v0
	v_mov_b32_e32 v5, v0
	v_mov_b32_e32 v6, v0
	v_mov_b32_e32 v7, v0
	v_mov_b32_e32 v16, v0
	v_mov_b32_e32 v17, v0
	v_mov_b32_e32 v18, v0
	v_mov_b32_e32 v19, v0
	v_mov_b32_e32 v20, v0
	v_mov_b32_e32 v21, v0
	v_mov_b32_e32 v22, v0
	v_mov_b32_e32 v23, v0
	v_mov_b32_e32 v32, v0
	v_mov_b32_e32 v33, v0
	v_mov_b32_e32 v34, v0
	v_mov_b32_e32 v35, v0
	v_mov_b32_e32 v36, v0
	v_mov_b32_e32 v37, v0
	v_mov_b32_e32 v38, v0
	v_mov_b32_e32 v39, v0
	v_mov_b32_e32 v48, v0
	v_mov_b32_e32 v49, v0
	v_mov_b32_e32 v50, v0
	v_mov_b32_e32 v51, v0
	v_mov_b32_e32 v52, v0
	v_mov_b32_e32 v53, v0
	v_mov_b32_e32 v54, v0
	v_mov_b32_e32 v55, v0
	v_mov_b32_e32 v8, v0
	v_mov_b32_e32 v9, v0
	v_mov_b32_e32 v10, v0
	v_mov_b32_e32 v11, v0
	v_mov_b32_e32 v12, v0
	v_mov_b32_e32 v13, v0
	v_mov_b32_e32 v14, v0
	v_mov_b32_e32 v15, v0
	v_mov_b32_e32 v24, v0
	v_mov_b32_e32 v25, v0
	v_mov_b32_e32 v26, v0
	v_mov_b32_e32 v27, v0
	v_mov_b32_e32 v28, v0
	v_mov_b32_e32 v29, v0
	v_mov_b32_e32 v30, v0
	v_mov_b32_e32 v31, v0
	v_mov_b32_e32 v40, v0
	v_mov_b32_e32 v41, v0
	v_mov_b32_e32 v42, v0
	v_mov_b32_e32 v43, v0
	v_mov_b32_e32 v44, v0
	v_mov_b32_e32 v45, v0
	v_mov_b32_e32 v46, v0
	v_mov_b32_e32 v47, v0
	v_mov_b32_e32 v56, v0
	v_mov_b32_e32 v57, v0
	v_mov_b32_e32 v58, v0
	v_mov_b32_e32 v59, v0
	v_mov_b32_e32 v60, v0
	v_mov_b32_e32 v61, v0
	v_mov_b32_e32 v62, v0
	v_mov_b32_e32 v63, v0
	v_mov_b32_e32 v64, v0
	v_mov_b32_e32 v65, v0
	v_mov_b32_e32 v66, v0
	v_mov_b32_e32 v67, v0
	v_mov_b32_e32 v68, v0
	v_mov_b32_e32 v69, v0
	v_mov_b32_e32 v70, v0
	v_mov_b32_e32 v71, v0
	v_mov_b32_e32 v80, v0
	v_mov_b32_e32 v81, v0
	v_mov_b32_e32 v82, v0
	v_mov_b32_e32 v83, v0
	v_mov_b32_e32 v84, v0
	v_mov_b32_e32 v85, v0
	v_mov_b32_e32 v86, v0
	v_mov_b32_e32 v87, v0
	v_mov_b32_e32 v96, v0
	v_mov_b32_e32 v97, v0
	v_mov_b32_e32 v98, v0
	v_mov_b32_e32 v99, v0
	v_mov_b32_e32 v100, v0
	v_mov_b32_e32 v101, v0
	v_mov_b32_e32 v102, v0
	v_mov_b32_e32 v103, v0
	v_mov_b32_e32 v112, v0
	v_mov_b32_e32 v113, v0
	v_mov_b32_e32 v114, v0
	v_mov_b32_e32 v115, v0
	v_mov_b32_e32 v116, v0
	v_mov_b32_e32 v117, v0
	v_mov_b32_e32 v118, v0
	v_mov_b32_e32 v119, v0
	v_mov_b32_e32 v72, v0
	v_mov_b32_e32 v73, v0
	v_mov_b32_e32 v74, v0
	v_mov_b32_e32 v75, v0
	v_mov_b32_e32 v76, v0
	v_mov_b32_e32 v77, v0
	v_mov_b32_e32 v78, v0
	v_mov_b32_e32 v79, v0
	v_mov_b32_e32 v88, v0
	v_mov_b32_e32 v89, v0
	v_mov_b32_e32 v90, v0
	v_mov_b32_e32 v91, v0
	v_mov_b32_e32 v92, v0
	v_mov_b32_e32 v93, v0
	v_mov_b32_e32 v94, v0
	v_mov_b32_e32 v95, v0
	v_mov_b32_e32 v104, v0
	v_mov_b32_e32 v105, v0
	v_mov_b32_e32 v106, v0
	v_mov_b32_e32 v107, v0
	v_mov_b32_e32 v108, v0
	v_mov_b32_e32 v109, v0
	v_mov_b32_e32 v110, v0
	v_mov_b32_e32 v111, v0
	v_mov_b32_e32 v120, v0
	v_mov_b32_e32 v121, v0
	v_mov_b32_e32 v122, v0
	v_mov_b32_e32 v123, v0
	v_mov_b32_e32 v124, v0
	v_mov_b32_e32 v125, v0
	v_mov_b32_e32 v126, v0
	v_mov_b32_e32 v127, v0
	v_add_u32_e32 v248, 0x18000, v162
	v_add_u32_e32 v249, 0x1c000, v162
	.p2align 6
